# P0 S5 table step: the 32 c_re/c_im loads issued at the top of the iteration with the parameter loads (spare VGPRs + copies) instead of after the first power computation; on top of v136
# baseline (speedup 1.0000x reference)
.LBB0_225:
	v_ashrrev_i32_e32 v8, 11, v20
	v_readlane_b32 s52, v254, 3
	v_ashrrev_i32_e32 v9, 31, v8
	v_readlane_b32 s66, v254, 17
	v_readlane_b32 s67, v254, 18
	v_readlane_b32 s64, v254, 15
	v_readlane_b32 s65, v254, 16
	v_lshl_add_u64 v[10:11], v[8:9], 2, s[66:67]
	global_load_dword v0, v[10:11], off
	v_lshlrev_b32_e32 v10, 6, v8
	v_or_b32_e32 v12, v10, v221
	v_ashrrev_i32_e32 v13, 31, v12
	v_lshlrev_b64 v[12:13], 2, v[12:13]
	v_lshl_add_u64 v[22:23], s[64:65], 0, v[12:13]
	global_load_dword v11, v[22:23], off
	v_readlane_b32 s62, v254, 13
	v_readlane_b32 s63, v254, 14
	v_readlane_b32 s53, v254, 4
	v_readlane_b32 s54, v254, 5
	v_lshl_add_u64 v[12:13], s[62:63], 0, v[12:13]
	global_load_dword v21, v[12:13], off
	v_lshl_or_b32 v182, v8, 10, v221
	v_ashrrev_i32_e32 v183, 31, v182
	v_lshlrev_b64 v[182:183], 2, v[182:183]
	v_lshl_add_u64 v[184:185], s[14:15], 0, v[182:183]
	v_lshl_add_u64 v[186:187], s[12:13], 0, v[182:183]
	global_load_dword v150, v[184:185], off
	global_load_dword v151, v[186:187], off
	global_load_dword v152, v[184:185], off offset:256
	global_load_dword v153, v[186:187], off offset:256
	global_load_dword v154, v[184:185], off offset:512
	global_load_dword v155, v[186:187], off offset:512
	global_load_dword v156, v[184:185], off offset:768
	global_load_dword v157, v[186:187], off offset:768
	global_load_dword v158, v[186:187], off offset:1024
	global_load_dword v159, v[186:187], off offset:1280
	global_load_dword v160, v[186:187], off offset:1536
	global_load_dword v161, v[186:187], off offset:1792
	global_load_dword v162, v[184:185], off offset:1024
	global_load_dword v163, v[184:185], off offset:1280
	global_load_dword v164, v[184:185], off offset:1536
	global_load_dword v165, v[184:185], off offset:1792
	global_load_dword v166, v[186:187], off offset:2048
	global_load_dword v167, v[186:187], off offset:2304
	global_load_dword v168, v[186:187], off offset:2560
	global_load_dword v169, v[186:187], off offset:2816
	global_load_dword v170, v[186:187], off offset:3072
	global_load_dword v171, v[186:187], off offset:3328
	global_load_dword v172, v[186:187], off offset:3584
	global_load_dword v173, v[186:187], off offset:3840
	global_load_dword v174, v[184:185], off offset:2048
	global_load_dword v175, v[184:185], off offset:2304
	global_load_dword v176, v[184:185], off offset:2560
	global_load_dword v177, v[184:185], off offset:2816
	global_load_dword v178, v[184:185], off offset:3072
	global_load_dword v179, v[184:185], off offset:3328
	global_load_dword v180, v[184:185], off offset:3584
	global_load_dword v181, v[184:185], off offset:3840
	v_readlane_b32 s55, v254, 6
	v_readlane_b32 s56, v254, 7
	v_readlane_b32 s57, v254, 8
	v_readlane_b32 s58, v254, 9
	v_readlane_b32 s59, v254, 10
	v_readlane_b32 s60, v254, 11
	v_readlane_b32 s61, v254, 12
	s_waitcnt vmcnt(34)
	v_mul_f32_e32 v9, 0x3fb8aa3b, v0
	v_fma_f32 v12, v0, s3, -v9
	v_rndne_f32_e32 v13, v9
	v_fmac_f32_e32 v12, 0x32a5705f, v0
	v_sub_f32_e32 v9, v9, v13
	v_add_f32_e32 v9, v9, v12
	v_cvt_i32_f32_e32 v22, v13
	v_exp_f32_e32 v9, v9
	v_cmp_ngt_f32_e32 vcc, s19, v0
	v_bfe_u32 v12, v20, 6, 5
	v_add_u32_e32 v13, 1, v12
	v_ldexp_f32 v9, v9, v22
	v_cndmask_b32_e32 v9, 0, v9, vcc
	v_cmp_nlt_f32_e32 vcc, s33, v0
	v_cvt_f32_ubyte0_e32 v13, v13
	s_nop 0
	v_cndmask_b32_e32 v9, v14, v9, vcc
	s_waitcnt vmcnt(33)
	v_mul_f32_e32 v0, v11, v9
	v_mul_f32_e32 v11, v0, v13
	v_and_b32_e32 v22, 0x7fffffff, v11
	v_cmp_nlt_f32_e64 s[0:1], |v11|, s36
	s_and_saveexec_b64 s[4:5], s[0:1]
	s_xor_b64 s[34:35], exec, s[4:5]
	s_cbranch_execz .LBB0_227
	v_lshrrev_b32_e32 v0, 23, v22
	v_add_u32_e32 v0, 0xffffff88, v0
	v_cmp_lt_u32_e32 vcc, 63, v0
	s_nop 1
	v_cndmask_b32_e32 v23, 0, v17, vcc
	v_add_u32_e32 v0, v23, v0
	v_cmp_lt_u32_e64 s[0:1], 31, v0
	s_nop 1
	v_cndmask_b32_e64 v23, 0, v18, s[0:1]
	v_add_u32_e32 v0, v23, v0
	v_cmp_lt_u32_e64 s[4:5], 31, v0
	s_nop 1
	v_cndmask_b32_e64 v23, 0, v18, s[4:5]
	v_add_u32_e32 v23, v23, v0
	v_and_b32_e32 v0, 0x7fffff, v22
	v_or_b32_e32 v36, 0x800000, v0
	v_mad_u64_u32 v[24:25], s[6:7], v36, s37, 0
	v_mov_b32_e32 v0, v25
	v_mad_u64_u32 v[26:27], s[6:7], v36, s38, v[0:1]
	v_mov_b32_e32 v0, v27
	v_mad_u64_u32 v[28:29], s[6:7], v36, s39, v[0:1]
	v_mov_b32_e32 v0, v29
	v_mad_u64_u32 v[30:31], s[6:7], v36, s40, v[0:1]
	v_mov_b32_e32 v0, v31
	v_mad_u64_u32 v[32:33], s[6:7], v36, s41, v[0:1]
	v_mov_b32_e32 v0, v33
	v_mad_u64_u32 v[34:35], s[6:7], v36, s42, v[0:1]
	v_mov_b32_e32 v0, v35
	v_mad_u64_u32 v[36:37], s[6:7], v36, s43, v[0:1]
	v_cndmask_b32_e32 v25, v34, v30, vcc
	v_cndmask_b32_e32 v0, v36, v32, vcc
	v_cndmask_b32_e32 v29, v37, v34, vcc
	v_cndmask_b32_e64 v27, v0, v25, s[0:1]
	v_cndmask_b32_e64 v0, v29, v0, s[0:1]
	v_cndmask_b32_e32 v29, v32, v28, vcc
	v_cndmask_b32_e64 v25, v25, v29, s[0:1]
	v_cndmask_b32_e64 v0, v0, v27, s[4:5]
	v_cndmask_b32_e64 v27, v27, v25, s[4:5]
	v_sub_u32_e32 v31, 32, v23
	v_alignbit_b32 v32, v0, v27, v31
	v_cmp_eq_u32_e64 s[6:7], 0, v23
	v_cndmask_b32_e32 v24, v28, v24, vcc
	s_nop 0
	v_cndmask_b32_e64 v23, v32, v0, s[6:7]
	v_cndmask_b32_e32 v0, v30, v26, vcc
	v_cndmask_b32_e64 v26, v29, v0, s[0:1]
	v_cndmask_b32_e64 v25, v25, v26, s[4:5]
	v_alignbit_b32 v29, v27, v25, v31
	v_cndmask_b32_e64 v27, v29, v27, s[6:7]
	v_bfe_u32 v32, v23, 29, 1
	v_cndmask_b32_e64 v0, v0, v24, s[0:1]
	v_alignbit_b32 v29, v23, v27, 30
	v_sub_u32_e32 v33, 0, v32
	v_cndmask_b32_e64 v0, v26, v0, s[4:5]
	v_xor_b32_e32 v29, v29, v33
	v_alignbit_b32 v24, v25, v0, v31
	v_cndmask_b32_e64 v24, v24, v25, s[6:7]
	v_ffbh_u32_e32 v26, v29
	v_alignbit_b32 v25, v27, v24, 30
	v_min_u32_e32 v26, 32, v26
	v_alignbit_b32 v0, v24, v0, 30
	v_xor_b32_e32 v25, v25, v33
	v_sub_u32_e32 v27, 31, v26
	v_xor_b32_e32 v0, v0, v33
	v_alignbit_b32 v28, v29, v25, v27
	v_alignbit_b32 v0, v25, v0, v27
	v_alignbit_b32 v24, v28, v0, 9
	v_ffbh_u32_e32 v25, v24
	v_min_u32_e32 v25, 32, v25
	v_lshrrev_b32_e32 v30, 29, v23
	v_not_b32_e32 v27, v25
	v_alignbit_b32 v0, v24, v0, v27
	v_lshlrev_b32_e32 v24, 31, v30
	v_or_b32_e32 v27, 0x33000000, v24
	v_add_lshl_u32 v25, v25, v26, 23
	v_lshrrev_b32_e32 v0, 9, v0
	v_sub_u32_e32 v25, v27, v25
	v_or_b32_e32 v24, 0.5, v24
	v_lshlrev_b32_e32 v26, 23, v26
	v_or_b32_e32 v0, v25, v0
	v_lshrrev_b32_e32 v25, 9, v28
	v_sub_u32_e32 v24, v24, v26
	v_or_b32_e32 v24, v25, v24
	v_mul_f32_e32 v25, 0x3fc90fda, v24
	v_fma_f32 v26, v24, s44, -v25
	v_fmac_f32_e32 v26, 0x33a22168, v24
	v_fmac_f32_e32 v26, 0x3fc90fda, v0
	v_lshrrev_b32_e32 v23, 30, v23
	v_add_f32_e32 v0, v25, v26
	v_add_u32_e32 v23, v32, v23
.LBB0_227:
	s_andn2_saveexec_b64 s[0:1], s[34:35]
	v_mul_f32_e64 v0, |v11|, s45
	v_rndne_f32_e32 v24, v0
	v_cvt_i32_f32_e32 v23, v24
	v_fma_f32 v0, v24, s46, |v11|
	v_fmac_f32_e32 v0, 0xb3a22168, v24
	v_fmac_f32_e32 v0, 0xa7c234c4, v24
	s_or_b64 exec, exec, s[0:1]
	v_lshl_or_b32 v24, v8, 10, v221
	v_ashrrev_i32_e32 v25, 31, v24
	v_lshlrev_b64 v[24:25], 2, v[24:25]
	v_lshl_add_u64 v[26:27], s[14:15], 0, v[24:25]
	s_waitcnt vmcnt(0)
	v_mov_b32_e32 v28, v150
	v_lshl_add_u64 v[24:25], s[12:13], 0, v[24:25]
	v_mov_b32_e32 v29, v151
	v_mov_b32_e32 v32, v152
	v_mov_b32_e32 v33, v153
	s_waitcnt vmcnt(4)
	v_max_f32_e32 v21, v21, v21
	v_mul_f32_e32 v30, v0, v0
	v_lshlrev_b32_e32 v34, 9, v8
	v_min_f32_e32 v21, 0xb8d1b717, v21
	v_fmamk_f32 v35, v30, 0xb94c1982, v15
	v_lshl_or_b32 v34, v12, 4, v34
	v_mul_f32_e32 v12, v21, v9
	v_fmaak_f32 v21, v30, v35, 0xbe2aaa9d
	v_mov_b32_e32 v35, v154
	v_mov_b32_e32 v38, v155
	v_fmamk_f32 v36, v30, 0x37d75334, v16
	v_fmaak_f32 v36, v30, v36, 0x3d2aabf7
	v_mul_f32_e32 v12, v12, v13
	v_mul_f32_e32 v13, v30, v21
	v_fmaak_f32 v21, v30, v36, 0xbf000004
	v_fmac_f32_e32 v0, v0, v13
	v_fma_f32 v13, v30, v21, 1.0
	v_mov_b32_e32 v21, v156
	v_mov_b32_e32 v30, v157
	v_mov_b32_e32 v39, v158
	v_mov_b32_e32 v40, v159
	v_mov_b32_e32 v41, v160
	v_mov_b32_e32 v42, v161
	v_mov_b32_e32 v43, v162
	v_mov_b32_e32 v44, v163
	v_mov_b32_e32 v45, v164
	v_mov_b32_e32 v46, v165
	v_mov_b32_e32 v47, v166
	v_mov_b32_e32 v48, v167
	v_mov_b32_e32 v49, v168
	v_mov_b32_e32 v50, v169
	v_mov_b32_e32 v51, v170
	v_mov_b32_e32 v52, v171
	v_mov_b32_e32 v53, v172
	s_nop 0
	v_mov_b32_e32 v24, v173
	s_nop 0
	v_mov_b32_e32 v25, v174
	v_mov_b32_e32 v54, v175
	v_mov_b32_e32 v55, v176
	v_mov_b32_e32 v56, v177
	v_mov_b32_e32 v57, v178
	v_mov_b32_e32 v58, v179
	v_mov_b32_e32 v59, v180
	s_nop 0
	v_mov_b32_e32 v26, v181
	v_lshlrev_b32_e32 v31, 30, v23
	v_and_b32_e32 v23, 1, v23
	v_mul_f32_e32 v36, 0x3fb8aa3b, v12
	v_fma_f32 v27, v12, s3, -v36
	v_rndne_f32_e32 v60, v36
	v_cmp_eq_u32_e32 vcc, 0, v23
	v_fmac_f32_e32 v27, 0x32a5705f, v12
	v_sub_f32_e32 v36, v36, v60
	v_cndmask_b32_e32 v23, v13, v0, vcc
	v_xor_b32_e32 v0, 0x80000000, v0
	v_cndmask_b32_e32 v0, v0, v13, vcc
	v_add_f32_e32 v13, v36, v27
	v_cvt_i32_f32_e32 v60, v60
	v_exp_f32_e32 v13, v13
	v_xor_b32_e32 v22, v22, v11
	v_and_b32_e32 v37, 0x80000000, v31
	v_xor_b32_e32 v22, v22, v23
	v_xor_b32_e32 v22, v22, v37
	v_bitop3_b32 v0, v0, v31, s47 bitop3:0x78
	v_cmp_class_f32_e64 vcc, v11, s48
	v_ldexp_f32 v13, v13, v60
	v_readlane_b32 s52, v254, 3
	v_cndmask_b32_e32 v0, v19, v0, vcc
	v_cndmask_b32_e32 v11, v19, v22, vcc
	v_cmp_ngt_f32_e32 vcc, s19, v12
	v_readlane_b32 s64, v254, 15
	v_readlane_b32 s65, v254, 16
	v_cndmask_b32_e32 v13, 0, v13, vcc
	v_cmp_nlt_f32_e32 vcc, s33, v12
	v_readlane_b32 s62, v254, 13
	v_readlane_b32 s63, v254, 14
	v_cndmask_b32_e32 v12, v14, v13, vcc
	v_mul_f32_e32 v27, v12, v11
	v_mul_f32_e32 v0, v12, v0
	v_readlane_b32 s53, v254, 4
	v_readlane_b32 s54, v254, 5
	v_readlane_b32 s55, v254, 6
	v_readlane_b32 s56, v254, 7
	v_readlane_b32 s57, v254, 8
	v_readlane_b32 s58, v254, 9
	v_readlane_b32 s59, v254, 10
	v_readlane_b32 s60, v254, 11
	v_readlane_b32 s61, v254, 12
	v_readlane_b32 s66, v254, 17
	v_readlane_b32 s67, v254, 18
	s_waitcnt vmcnt(31)
	v_mul_f32_e32 v11, v27, v28
	v_mul_f32_e32 v22, v0, v28
	s_waitcnt vmcnt(30)
	v_fma_f32 v11, v0, v29, -v11
	v_fmac_f32_e32 v22, v27, v29
	v_cvt_pk_bf16_f32 v11, v11, s0
	v_mad_i64_i32 v[12:13], s[0:1], v34, s49, v[6:7]
	global_store_short v[12:13], v11, off offset:1024
	s_nop 0
	v_cvt_pk_bf16_f32 v11, -v22, s0
	global_store_short v[12:13], v11, off offset:1152
	s_waitcnt vmcnt(31)
	v_mul_f32_e32 v11, v27, v32
	s_waitcnt vmcnt(30)
	v_fma_f32 v11, v0, v33, -v11
	v_mul_f32_e32 v22, v0, v32
	v_or_b32_e32 v12, 1, v34
	v_fmac_f32_e32 v22, v27, v33
	v_cvt_pk_bf16_f32 v11, v11, s0
	v_mad_i64_i32 v[12:13], s[0:1], v12, s49, v[6:7]
	global_store_short v[12:13], v11, off offset:1024
	s_nop 0
	v_cvt_pk_bf16_f32 v11, -v22, s0
	global_store_short v[12:13], v11, off offset:1152
	s_waitcnt vmcnt(31)
	v_mul_f32_e32 v11, v27, v35
	s_waitcnt vmcnt(30)
	v_fma_f32 v11, v0, v38, -v11
	v_mul_f32_e32 v22, v0, v35
	v_or_b32_e32 v12, 2, v34
	v_fmac_f32_e32 v22, v27, v38
	v_cvt_pk_bf16_f32 v11, v11, s0
	v_mad_i64_i32 v[12:13], s[0:1], v12, s49, v[6:7]
	global_store_short v[12:13], v11, off offset:1024
	s_nop 0
	v_cvt_pk_bf16_f32 v11, -v22, s0
	global_store_short v[12:13], v11, off offset:1152
	s_waitcnt vmcnt(31)
	v_mul_f32_e32 v11, v27, v21
	s_waitcnt vmcnt(30)
	v_fma_f32 v11, v0, v30, -v11
	v_mul_f32_e32 v21, v0, v21
	v_or_b32_e32 v12, 3, v34
	v_fmac_f32_e32 v21, v27, v30
	v_cvt_pk_bf16_f32 v11, v11, s0
	v_mad_i64_i32 v[12:13], s[0:1], v12, s49, v[6:7]
	global_store_short v[12:13], v11, off offset:1024
	s_nop 0
	v_cvt_pk_bf16_f32 v11, -v21, s0
	global_store_short v[12:13], v11, off offset:1152
	s_waitcnt vmcnt(27)
	v_mul_f32_e32 v11, v27, v43
	v_fma_f32 v11, v0, v39, -v11
	v_mul_f32_e32 v21, v0, v43
	v_or_b32_e32 v12, 4, v34
	v_fmac_f32_e32 v21, v27, v39
	v_cvt_pk_bf16_f32 v11, v11, s0
	v_mad_i64_i32 v[12:13], s[0:1], v12, s49, v[6:7]
	global_store_short v[12:13], v11, off offset:1024
	s_nop 0
	v_cvt_pk_bf16_f32 v11, -v21, s0
	global_store_short v[12:13], v11, off offset:1152
	s_waitcnt vmcnt(28)
	v_mul_f32_e32 v11, v27, v44
	v_fma_f32 v11, v0, v40, -v11
	v_mul_f32_e32 v21, v0, v44
	v_or_b32_e32 v12, 5, v34
	v_fmac_f32_e32 v21, v27, v40
	v_cvt_pk_bf16_f32 v11, v11, s0
	v_mad_i64_i32 v[12:13], s[0:1], v12, s49, v[6:7]
	global_store_short v[12:13], v11, off offset:1024
	s_nop 0
	v_cvt_pk_bf16_f32 v11, -v21, s0
	global_store_short v[12:13], v11, off offset:1152
	s_waitcnt vmcnt(29)
	v_mul_f32_e32 v11, v27, v45
	v_fma_f32 v11, v0, v41, -v11
	v_mul_f32_e32 v21, v0, v45
	v_or_b32_e32 v12, 6, v34
	v_fmac_f32_e32 v21, v27, v41
	v_cvt_pk_bf16_f32 v11, v11, s0
	v_mad_i64_i32 v[12:13], s[0:1], v12, s49, v[6:7]
	global_store_short v[12:13], v11, off offset:1024
	s_nop 0
	v_cvt_pk_bf16_f32 v11, -v21, s0
	global_store_short v[12:13], v11, off offset:1152
	s_waitcnt vmcnt(30)
	v_mul_f32_e32 v11, v27, v46
	v_fma_f32 v11, v0, v42, -v11
	v_mul_f32_e32 v21, v0, v46
	v_or_b32_e32 v12, 7, v34
	v_fmac_f32_e32 v21, v27, v42
	v_cvt_pk_bf16_f32 v11, v11, s0
	v_mad_i64_i32 v[12:13], s[0:1], v12, s49, v[6:7]
	global_store_short v[12:13], v11, off offset:1024
	s_nop 0
	v_cvt_pk_bf16_f32 v11, -v21, s0
	global_store_short v[12:13], v11, off offset:1152
	s_waitcnt vmcnt(23)
	v_mul_f32_e32 v11, v27, v25
	v_fma_f32 v11, v0, v47, -v11
	v_mul_f32_e32 v21, v0, v25
	v_or_b32_e32 v12, 8, v34
	v_fmac_f32_e32 v21, v27, v47
	v_cvt_pk_bf16_f32 v11, v11, s0
	v_mad_i64_i32 v[12:13], s[0:1], v12, s49, v[6:7]
	global_store_short v[12:13], v11, off offset:1024
	s_nop 0
	v_cvt_pk_bf16_f32 v11, -v21, s0
	v_bfe_u32 v21, v20, 5, 6
	global_store_short v[12:13], v11, off offset:1152
	v_or_b32_e32 v12, v10, v21
	v_ashrrev_i32_e32 v13, 31, v12
	v_lshlrev_b64 v[22:23], 2, v[12:13]
	v_lshl_add_u64 v[10:11], s[64:65], 0, v[22:23]
	global_load_dword v11, v[10:11], off
	s_waitcnt vmcnt(25)
	v_mul_f32_e32 v10, v27, v54
	v_lshl_add_u64 v[22:23], s[62:63], 0, v[22:23]
	v_fma_f32 v13, v0, v48, -v10
	global_load_dword v10, v[22:23], off
	v_mul_f32_e32 v25, v0, v54
	v_or_b32_e32 v22, 9, v34
	v_fmac_f32_e32 v25, v27, v48
	v_cvt_pk_bf16_f32 v13, v13, s0
	v_mad_i64_i32 v[22:23], s[0:1], v22, s49, v[6:7]
	global_store_short v[22:23], v13, off offset:1024
	s_nop 0
	v_cvt_pk_bf16_f32 v13, -v25, s0
	global_store_short v[22:23], v13, off offset:1152
	s_waitcnt vmcnt(27)
	v_mul_f32_e32 v13, v27, v55
	v_fma_f32 v13, v0, v49, -v13
	v_mul_f32_e32 v25, v0, v55
	v_or_b32_e32 v22, 10, v34
	v_fmac_f32_e32 v25, v27, v49
	v_cvt_pk_bf16_f32 v13, v13, s0
	v_mad_i64_i32 v[22:23], s[0:1], v22, s49, v[6:7]
	global_store_short v[22:23], v13, off offset:1024
	s_nop 0
	v_cvt_pk_bf16_f32 v13, -v25, s0
	global_store_short v[22:23], v13, off offset:1152
	s_waitcnt vmcnt(28)
	v_mul_f32_e32 v13, v27, v56
	v_fma_f32 v13, v0, v50, -v13
	v_mul_f32_e32 v25, v0, v56
	v_or_b32_e32 v22, 11, v34
	v_fmac_f32_e32 v25, v27, v50
	v_cvt_pk_bf16_f32 v13, v13, s0
	v_mad_i64_i32 v[22:23], s[0:1], v22, s49, v[6:7]
	global_store_short v[22:23], v13, off offset:1024
	s_nop 0
	v_cvt_pk_bf16_f32 v13, -v25, s0
	global_store_short v[22:23], v13, off offset:1152
	s_waitcnt vmcnt(29)
	v_mul_f32_e32 v13, v27, v57
	v_fma_f32 v13, v0, v51, -v13
	v_mul_f32_e32 v25, v0, v57
	v_or_b32_e32 v22, 12, v34
	v_fmac_f32_e32 v25, v27, v51
	v_cvt_pk_bf16_f32 v13, v13, s0
	v_mad_i64_i32 v[22:23], s[0:1], v22, s49, v[6:7]
	global_store_short v[22:23], v13, off offset:1024
	s_nop 0
	v_cvt_pk_bf16_f32 v13, -v25, s0
	global_store_short v[22:23], v13, off offset:1152
	s_waitcnt vmcnt(30)
	v_mul_f32_e32 v13, v27, v58
	v_fma_f32 v13, v0, v52, -v13
	v_mul_f32_e32 v25, v0, v58
	v_or_b32_e32 v22, 13, v34
	v_fmac_f32_e32 v25, v27, v52
	v_cvt_pk_bf16_f32 v13, v13, s0
	v_mad_i64_i32 v[22:23], s[0:1], v22, s49, v[6:7]
	global_store_short v[22:23], v13, off offset:1024
	s_nop 0
	v_cvt_pk_bf16_f32 v13, -v25, s0
	global_store_short v[22:23], v13, off offset:1152
	s_waitcnt vmcnt(31)
	v_mul_f32_e32 v13, v27, v59
	v_fma_f32 v13, v0, v53, -v13
	v_mul_f32_e32 v25, v0, v59
	v_or_b32_e32 v22, 14, v34
	v_fmac_f32_e32 v25, v27, v53
	v_cvt_pk_bf16_f32 v13, v13, s0
	v_mad_i64_i32 v[22:23], s[0:1], v22, s49, v[6:7]
	global_store_short v[22:23], v13, off offset:1024
	s_nop 0
	v_cvt_pk_bf16_f32 v13, -v25, s0
	global_store_short v[22:23], v13, off offset:1152
	s_waitcnt vmcnt(32)
	v_mul_f32_e32 v13, v27, v26
	v_fma_f32 v13, v0, v24, -v13
	v_mul_f32_e32 v0, v0, v26
	v_or_b32_e32 v22, 15, v34
	v_fmac_f32_e32 v0, v27, v24
	v_cvt_pk_bf16_f32 v13, v13, s0
	v_mad_i64_i32 v[22:23], s[0:1], v22, s49, v[6:7]
	global_store_short v[22:23], v13, off offset:1024
	s_nop 0
	v_cvt_pk_bf16_f32 v0, -v0, s0
	global_store_short v[22:23], v0, off offset:1152
	s_waitcnt vmcnt(15)
	v_mul_f32_e32 v13, v9, v11
	v_mul_f32_e32 v22, v13, v5
	v_and_b32_e32 v23, 0x7fffffff, v22
	v_cmp_nlt_f32_e64 s[0:1], |v22|, s36
	s_and_saveexec_b64 s[4:5], s[0:1]
	s_xor_b64 s[34:35], exec, s[4:5]
	s_cbranch_execz .LBB0_231
	v_lshrrev_b32_e32 v0, 23, v23
	v_add_u32_e32 v0, 0xffffff88, v0
	v_cmp_lt_u32_e32 vcc, 63, v0
	s_nop 1
	v_cndmask_b32_e32 v24, 0, v17, vcc
	v_add_u32_e32 v0, v24, v0
	v_cmp_lt_u32_e64 s[0:1], 31, v0
	s_nop 1
	v_cndmask_b32_e64 v24, 0, v18, s[0:1]
	v_add_u32_e32 v0, v24, v0
	v_cmp_lt_u32_e64 s[4:5], 31, v0
	s_nop 1
	v_cndmask_b32_e64 v24, 0, v18, s[4:5]
	v_add_u32_e32 v38, v24, v0
	v_and_b32_e32 v0, 0x7fffff, v23
	v_or_b32_e32 v36, 0x800000, v0
	v_mad_u64_u32 v[24:25], s[6:7], v36, s37, 0
	v_mov_b32_e32 v0, v25
	v_mad_u64_u32 v[26:27], s[6:7], v36, s38, v[0:1]
	v_mov_b32_e32 v0, v27
	v_mad_u64_u32 v[28:29], s[6:7], v36, s39, v[0:1]
	v_mov_b32_e32 v0, v29
	v_mad_u64_u32 v[30:31], s[6:7], v36, s40, v[0:1]
	v_mov_b32_e32 v0, v31
	v_mad_u64_u32 v[32:33], s[6:7], v36, s41, v[0:1]
	v_mov_b32_e32 v0, v33
	v_mad_u64_u32 v[34:35], s[6:7], v36, s42, v[0:1]
	v_mov_b32_e32 v0, v35
	v_mad_u64_u32 v[36:37], s[6:7], v36, s43, v[0:1]
	v_cndmask_b32_e32 v25, v34, v30, vcc
	v_cndmask_b32_e32 v0, v36, v32, vcc
	v_cndmask_b32_e32 v29, v37, v34, vcc
	v_cndmask_b32_e64 v27, v0, v25, s[0:1]
	v_cndmask_b32_e64 v0, v29, v0, s[0:1]
	v_cndmask_b32_e32 v29, v32, v28, vcc
	v_cndmask_b32_e64 v25, v25, v29, s[0:1]
	v_cndmask_b32_e32 v26, v30, v26, vcc
	v_cndmask_b32_e64 v0, v0, v27, s[4:5]
	v_cndmask_b32_e64 v27, v27, v25, s[4:5]
	v_sub_u32_e32 v31, 32, v38
	v_cndmask_b32_e64 v29, v29, v26, s[0:1]
	v_alignbit_b32 v32, v0, v27, v31
	v_cmp_eq_u32_e64 s[6:7], 0, v38
	v_cndmask_b32_e64 v25, v25, v29, s[4:5]
	v_cndmask_b32_e32 v24, v28, v24, vcc
	v_cndmask_b32_e64 v0, v32, v0, s[6:7]
	v_alignbit_b32 v30, v27, v25, v31
	v_cndmask_b32_e64 v24, v26, v24, s[0:1]
	v_cndmask_b32_e64 v27, v30, v27, s[6:7]
	v_bfe_u32 v33, v0, 29, 1
	v_cndmask_b32_e64 v24, v29, v24, s[4:5]
	v_alignbit_b32 v30, v0, v27, 30
	v_sub_u32_e32 v34, 0, v33
	v_alignbit_b32 v26, v25, v24, v31
	v_xor_b32_e32 v30, v30, v34
	v_cndmask_b32_e64 v25, v26, v25, s[6:7]
	v_alignbit_b32 v26, v27, v25, 30
	v_ffbh_u32_e32 v27, v30
	v_min_u32_e32 v27, 32, v27
	v_alignbit_b32 v24, v25, v24, 30
	v_xor_b32_e32 v26, v26, v34
	v_sub_u32_e32 v28, 31, v27
	v_xor_b32_e32 v24, v24, v34
	v_alignbit_b32 v29, v30, v26, v28
	v_alignbit_b32 v24, v26, v24, v28
	v_alignbit_b32 v25, v29, v24, 9
	v_ffbh_u32_e32 v26, v25
	v_min_u32_e32 v26, 32, v26
	v_lshrrev_b32_e32 v32, 29, v0
	v_not_b32_e32 v28, v26
	v_alignbit_b32 v24, v25, v24, v28
	v_lshlrev_b32_e32 v25, 31, v32
	v_or_b32_e32 v28, 0x33000000, v25
	v_add_lshl_u32 v26, v26, v27, 23
	v_lshrrev_b32_e32 v24, 9, v24
	v_sub_u32_e32 v26, v28, v26
	v_or_b32_e32 v25, 0.5, v25
	v_lshlrev_b32_e32 v27, 23, v27
	v_or_b32_e32 v24, v26, v24
	v_lshrrev_b32_e32 v26, 9, v29
	v_sub_u32_e32 v25, v25, v27
	v_or_b32_e32 v25, v26, v25
	v_mul_f32_e32 v26, 0x3fc90fda, v25
	v_fma_f32 v27, v25, s44, -v26
	v_fmac_f32_e32 v27, 0x33a22168, v25
	v_fmac_f32_e32 v27, 0x3fc90fda, v24
	v_lshrrev_b32_e32 v0, 30, v0
	v_add_f32_e32 v25, v26, v27
	v_add_u32_e32 v26, v33, v0
